# prep0: nt (non-temporal) policy on the once-read f32 weight loads (adaLN GEMV weights and the transpose tile loads)
# speedup vs baseline: 1.0211x; 1.0211x over previous
.LBB0_864:
	s_mul_hi_i32 s0, s33, 0x2aaaaaab
	s_lshr_b32 s1, s0, 31
	s_ashr_i32 s36, s0, 5
	s_add_i32 s36, s36, s1
	s_mul_i32 s0, s36, 0xc0
	v_readlane_b32 s40, v254, 5
	s_sub_i32 s0, s33, s0
	s_mul_i32 s2, s36, 0x1800000
	v_readlane_b32 s50, v254, 15
	s_mul_hi_i32 s1, s36, 0x1800000
	v_readlane_b32 s51, v254, 16
	s_add_u32 s2, s50, s2
	v_mov_b32_e32 v140, v229
	s_addc_u32 s3, s51, s1
	s_lshl_b32 s0, s0, 5
	v_ashrrev_i32_e32 v141, 3, v140
	v_lshlrev_b32_e32 v2, 5, v141
	v_mov_b64_e32 v[0:1], s[2:3]
	s_movk_i32 s28, 0x6000
	v_mad_i64_i32 v[0:1], s[2:3], v2, s28, v[0:1]
	s_ashr_i32 s1, s0, 31
	v_lshlrev_b32_e32 v2, 4, v140
	v_lshl_add_u64 v[0:1], s[0:1], 2, v[0:1]
	v_and_b32_e32 v200, 0x70, v2
	v_lshl_add_u64 v[0:1], v[0:1], 0, v[200:201]
	v_add_co_u32_e32 v2, vcc, s28, v0
	s_mov_b32 s2, 0xc000
	s_nop 0
	v_addc_co_u32_e32 v3, vcc, 0, v1, vcc
	global_load_dwordx4 v[132:135], v[0:1], off nt
	global_load_dwordx4 v[136:139], v[2:3], off nt
	v_add_co_u32_e32 v2, vcc, s2, v0
	s_mov_b32 s2, 0x12000
	s_nop 0
	v_addc_co_u32_e32 v3, vcc, 0, v1, vcc
	global_load_dwordx4 v[128:131], v[2:3], off nt
	v_add_co_u32_e32 v2, vcc, s2, v0
	s_mov_b32 s2, 0x18000
	s_nop 0
	v_addc_co_u32_e32 v3, vcc, 0, v1, vcc
	global_load_dwordx4 v[124:127], v[2:3], off nt
	v_add_co_u32_e32 v2, vcc, s2, v0
	s_mov_b32 s2, 0x1e000
	s_nop 0
	v_addc_co_u32_e32 v3, vcc, 0, v1, vcc
	global_load_dwordx4 v[108:111], v[2:3], off nt
	v_add_co_u32_e32 v2, vcc, s2, v0
	s_mov_b32 s2, 0x24000
	s_nop 0
	v_addc_co_u32_e32 v3, vcc, 0, v1, vcc
	global_load_dwordx4 v[112:115], v[2:3], off nt
	v_add_co_u32_e32 v2, vcc, s2, v0
	s_mov_b32 s2, 0x2a000
	s_nop 0
	v_addc_co_u32_e32 v3, vcc, 0, v1, vcc
	global_load_dwordx4 v[104:107], v[2:3], off nt
	v_add_co_u32_e32 v2, vcc, s2, v0
	s_mov_b32 s2, 0x30000
	s_nop 0
	v_addc_co_u32_e32 v3, vcc, 0, v1, vcc
	global_load_dwordx4 v[100:103], v[2:3], off nt
	v_add_co_u32_e32 v2, vcc, s2, v0
	s_mov_b32 s2, 0x36000
	s_nop 0
	v_addc_co_u32_e32 v3, vcc, 0, v1, vcc
	global_load_dwordx4 v[92:95], v[2:3], off nt
	v_add_co_u32_e32 v2, vcc, s2, v0
	s_mov_b32 s2, 0x3c000
	s_nop 0
	v_addc_co_u32_e32 v3, vcc, 0, v1, vcc
	global_load_dwordx4 v[96:99], v[2:3], off nt
	v_add_co_u32_e32 v2, vcc, s2, v0
	s_mov_b32 s2, 0x42000
	s_nop 0
	v_addc_co_u32_e32 v3, vcc, 0, v1, vcc
	global_load_dwordx4 v[88:91], v[2:3], off nt
	v_add_co_u32_e32 v2, vcc, s2, v0
	s_mov_b32 s2, 0x48000
	s_nop 0
	v_addc_co_u32_e32 v3, vcc, 0, v1, vcc
	global_load_dwordx4 v[84:87], v[2:3], off nt
	v_add_co_u32_e32 v2, vcc, s2, v0
	s_mov_b32 s2, 0x4e000
	s_nop 0
	v_addc_co_u32_e32 v3, vcc, 0, v1, vcc
	global_load_dwordx4 v[72:75], v[2:3], off nt
	v_add_co_u32_e32 v2, vcc, s2, v0
	s_mov_b32 s2, 0x54000
	s_nop 0
	v_addc_co_u32_e32 v3, vcc, 0, v1, vcc
	global_load_dwordx4 v[76:79], v[2:3], off nt
	v_add_co_u32_e32 v2, vcc, s2, v0
	s_mov_b32 s2, 0x5a000
	s_nop 0
	v_addc_co_u32_e32 v3, vcc, 0, v1, vcc
	global_load_dwordx4 v[68:71], v[2:3], off nt
	v_add_co_u32_e32 v2, vcc, s2, v0
	s_mov_b32 s2, 0x60000
	s_nop 0
	v_addc_co_u32_e32 v3, vcc, 0, v1, vcc
	global_load_dwordx4 v[64:67], v[2:3], off nt
	v_add_co_u32_e32 v2, vcc, s2, v0
	s_mov_b32 s2, 0x66000
	s_nop 0
	v_addc_co_u32_e32 v3, vcc, 0, v1, vcc
	global_load_dwordx4 v[56:59], v[2:3], off nt
	v_add_co_u32_e32 v2, vcc, s2, v0
	s_mov_b32 s2, 0x6c000
	s_nop 0
	v_addc_co_u32_e32 v3, vcc, 0, v1, vcc
	global_load_dwordx4 v[60:63], v[2:3], off nt
	v_add_co_u32_e32 v2, vcc, s2, v0
	s_mov_b32 s2, 0x72000
	s_nop 0
	v_addc_co_u32_e32 v3, vcc, 0, v1, vcc
	global_load_dwordx4 v[52:55], v[2:3], off nt
	v_add_co_u32_e32 v2, vcc, s2, v0
	s_mov_b32 s2, 0x78000
	s_nop 0
	v_addc_co_u32_e32 v3, vcc, 0, v1, vcc
	global_load_dwordx4 v[48:51], v[2:3], off nt
	v_add_co_u32_e32 v2, vcc, s2, v0
	s_mov_b32 s2, 0x7e000
	s_nop 0
	v_addc_co_u32_e32 v3, vcc, 0, v1, vcc
	global_load_dwordx4 v[40:43], v[2:3], off nt
	v_add_co_u32_e32 v2, vcc, s2, v0
	s_mov_b32 s2, 0x84000
	s_nop 0
	v_addc_co_u32_e32 v3, vcc, 0, v1, vcc
	global_load_dwordx4 v[44:47], v[2:3], off nt
	v_add_co_u32_e32 v2, vcc, s2, v0
	s_mov_b32 s2, 0x8a000
	s_nop 0
	v_addc_co_u32_e32 v3, vcc, 0, v1, vcc
	global_load_dwordx4 v[36:39], v[2:3], off nt
	v_add_co_u32_e32 v2, vcc, s2, v0
	s_mov_b32 s2, 0x90000
	s_nop 0
	v_addc_co_u32_e32 v3, vcc, 0, v1, vcc
	global_load_dwordx4 v[32:35], v[2:3], off nt
	v_add_co_u32_e32 v2, vcc, s2, v0
	s_mov_b32 s2, 0x96000
	s_nop 0
	v_addc_co_u32_e32 v3, vcc, 0, v1, vcc
	global_load_dwordx4 v[24:27], v[2:3], off nt
	v_add_co_u32_e32 v2, vcc, s2, v0
	s_mov_b32 s2, 0x9c000
	s_nop 0
	v_addc_co_u32_e32 v3, vcc, 0, v1, vcc
	global_load_dwordx4 v[28:31], v[2:3], off nt
	v_add_co_u32_e32 v2, vcc, s2, v0
	s_mov_b32 s2, 0xa2000
	s_nop 0
	v_addc_co_u32_e32 v3, vcc, 0, v1, vcc
	global_load_dwordx4 v[20:23], v[2:3], off nt
	v_add_co_u32_e32 v2, vcc, s2, v0
	s_mov_b32 s2, 0xa8000
	s_nop 0
	v_addc_co_u32_e32 v3, vcc, 0, v1, vcc
	global_load_dwordx4 v[16:19], v[2:3], off nt
	v_add_co_u32_e32 v2, vcc, s2, v0
	s_mov_b32 s2, 0xae000
	s_nop 0
	v_addc_co_u32_e32 v3, vcc, 0, v1, vcc
	global_load_dwordx4 v[8:11], v[2:3], off nt
	v_add_co_u32_e32 v2, vcc, s2, v0
	s_mov_b32 s2, 0xb4000
	s_nop 0
	v_addc_co_u32_e32 v3, vcc, 0, v1, vcc
	global_load_dwordx4 v[12:15], v[2:3], off nt
	v_add_co_u32_e32 v2, vcc, s2, v0
	s_mov_b32 s2, 0xba000
	s_nop 0
	v_addc_co_u32_e32 v3, vcc, 0, v1, vcc
	v_add_co_u32_e32 v0, vcc, s2, v0
	v_lshl_add_u32 v142, v141, 7, s69
	s_nop 0
	v_addc_co_u32_e32 v1, vcc, 0, v1, vcc
	global_load_dwordx4 v[4:7], v[2:3], off nt
	s_movk_i32 s2, 0x280
	global_load_dwordx4 v[0:3], v[0:1], off nt
	ds_read_b128 v[144:147], v142
	ds_read_b128 v[120:123], v142 offset:16
	ds_read_b128 v[116:119], v142 offset:32
	ds_read_b128 v[80:83], v142 offset:48
	ds_read_b128 v[148:151], v142 offset:4096
	ds_read_b128 v[152:155], v142 offset:8192
	ds_read_b128 v[156:159], v142 offset:12288
	ds_read_b128 v[160:163], v142 offset:16384
	s_waitcnt vmcnt(31) lgkmcnt(7)
	v_pk_fma_f32 v[164:165], v[134:135], v[144:145], 0 op_sel_hi:[1,0,0]
	v_pk_fma_f32 v[166:167], v[132:133], v[144:145], 0 op_sel_hi:[1,0,0]
	s_waitcnt lgkmcnt(3)
	v_pk_fma_f32 v[168:169], v[134:135], v[148:149], 0 op_sel_hi:[1,0,0]
	v_pk_fma_f32 v[170:171], v[132:133], v[148:149], 0 op_sel_hi:[1,0,0]
	s_waitcnt lgkmcnt(2)
	v_pk_fma_f32 v[172:173], v[134:135], v[152:153], 0 op_sel_hi:[1,0,0]
	v_pk_fma_f32 v[174:175], v[132:133], v[152:153], 0 op_sel_hi:[1,0,0]
	s_waitcnt lgkmcnt(1)
	v_pk_fma_f32 v[176:177], v[134:135], v[156:157], 0 op_sel_hi:[1,0,0]
	v_pk_fma_f32 v[178:179], v[132:133], v[156:157], 0 op_sel_hi:[1,0,0]
	s_waitcnt lgkmcnt(0)
	v_pk_fma_f32 v[132:133], v[132:133], v[160:161], 0 op_sel_hi:[1,0,0]
	v_pk_fma_f32 v[134:135], v[134:135], v[160:161], 0 op_sel_hi:[1,0,0]
	s_waitcnt vmcnt(30)
	v_pk_fma_f32 v[164:165], v[138:139], v[144:145], v[164:165] op_sel:[0,1,0]
	v_pk_fma_f32 v[144:145], v[136:137], v[144:145], v[166:167] op_sel:[0,1,0]
	v_pk_fma_f32 v[166:167], v[138:139], v[148:149], v[168:169] op_sel:[0,1,0]
	v_pk_fma_f32 v[148:149], v[136:137], v[148:149], v[170:171] op_sel:[0,1,0]
	v_pk_fma_f32 v[168:169], v[138:139], v[152:153], v[172:173] op_sel:[0,1,0]
	v_pk_fma_f32 v[152:153], v[136:137], v[152:153], v[174:175] op_sel:[0,1,0]
	v_pk_fma_f32 v[170:171], v[138:139], v[156:157], v[176:177] op_sel:[0,1,0]
	v_pk_fma_f32 v[156:157], v[136:137], v[156:157], v[178:179] op_sel:[0,1,0]
	v_pk_fma_f32 v[132:133], v[136:137], v[160:161], v[132:133] op_sel:[0,1,0]
	v_pk_fma_f32 v[134:135], v[138:139], v[160:161], v[134:135] op_sel:[0,1,0]
	s_waitcnt vmcnt(29)
	v_pk_fma_f32 v[136:137], v[130:131], v[146:147], v[164:165] op_sel_hi:[1,0,1]
	v_pk_fma_f32 v[138:139], v[128:129], v[146:147], v[144:145] op_sel_hi:[1,0,1]
	v_pk_fma_f32 v[148:149], v[128:129], v[150:151], v[148:149] op_sel_hi:[1,0,1]
	v_pk_fma_f32 v[152:153], v[128:129], v[154:155], v[152:153] op_sel_hi:[1,0,1]
	v_pk_fma_f32 v[156:157], v[128:129], v[158:159], v[156:157] op_sel_hi:[1,0,1]
	v_pk_fma_f32 v[132:133], v[128:129], v[162:163], v[132:133] op_sel_hi:[1,0,1]
	v_mov_b32_e32 v128, v147
	v_pk_fma_f32 v[144:145], v[130:131], v[150:151], v[166:167] op_sel_hi:[1,0,1]
	v_pk_fma_f32 v[160:161], v[130:131], v[154:155], v[168:169] op_sel_hi:[1,0,1]
	v_pk_fma_f32 v[164:165], v[130:131], v[158:159], v[170:171] op_sel_hi:[1,0,1]
	v_pk_fma_f32 v[130:131], v[130:131], v[162:163], v[134:135] op_sel_hi:[1,0,1]
	s_waitcnt vmcnt(28)
	v_pk_fma_f32 v[134:135], v[126:127], v[128:129], v[136:137] op_sel_hi:[1,0,1]
	v_pk_fma_f32 v[136:137], v[124:125], v[128:129], v[138:139] op_sel_hi:[1,0,1]
	v_mov_b32_e32 v128, v151
	v_pk_fma_f32 v[138:139], v[126:127], v[128:129], v[144:145] op_sel_hi:[1,0,1]
	v_pk_fma_f32 v[144:145], v[124:125], v[128:129], v[148:149] op_sel_hi:[1,0,1]
	v_mov_b32_e32 v128, v155
	v_pk_fma_f32 v[146:147], v[126:127], v[128:129], v[160:161] op_sel_hi:[1,0,1]
	v_pk_fma_f32 v[148:149], v[124:125], v[128:129], v[152:153] op_sel_hi:[1,0,1]
	v_mov_b32_e32 v128, v159
	v_mov_b32_e32 v154, v163
	v_pk_fma_f32 v[150:151], v[126:127], v[128:129], v[164:165] op_sel_hi:[1,0,1]
	v_pk_fma_f32 v[152:153], v[124:125], v[128:129], v[156:157] op_sel_hi:[1,0,1]
	v_pk_fma_f32 v[128:129], v[126:127], v[154:155], v[130:131] op_sel_hi:[1,0,1]
	v_pk_fma_f32 v[130:131], v[124:125], v[154:155], v[132:133] op_sel_hi:[1,0,1]
	s_waitcnt vmcnt(27)
	v_pk_fma_f32 v[124:125], v[110:111], v[120:121], v[134:135] op_sel_hi:[1,0,1]
	ds_read_b128 v[132:135], v142 offset:4112
	v_pk_fma_f32 v[126:127], v[108:109], v[120:121], v[136:137] op_sel_hi:[1,0,1]
	s_waitcnt vmcnt(26)
	v_pk_fma_f32 v[124:125], v[114:115], v[120:121], v[124:125] op_sel:[0,1,0]
	v_pk_fma_f32 v[120:121], v[112:113], v[120:121], v[126:127] op_sel:[0,1,0]
	s_movk_i32 s37, 0x6000
	s_waitcnt lgkmcnt(0)
	v_pk_fma_f32 v[154:155], v[110:111], v[132:133], v[138:139] op_sel_hi:[1,0,1]
	ds_read_b128 v[136:139], v142 offset:8208
	v_pk_fma_f32 v[156:157], v[108:109], v[132:133], v[144:145] op_sel_hi:[1,0,1]
	v_pk_fma_f32 v[126:127], v[114:115], v[132:133], v[154:155] op_sel:[0,1,0]
	v_readlane_b32 s41, v254, 6
	v_readlane_b32 s42, v254, 7
	s_waitcnt lgkmcnt(0)
	v_pk_fma_f32 v[158:159], v[110:111], v[136:137], v[146:147] op_sel_hi:[1,0,1]
	ds_read_b128 v[144:147], v142 offset:12304
	v_pk_fma_f32 v[160:161], v[108:109], v[136:137], v[148:149] op_sel_hi:[1,0,1]
	v_readlane_b32 s43, v254, 8
	v_readlane_b32 s44, v254, 9
	v_readlane_b32 s45, v254, 10
	s_waitcnt lgkmcnt(0)
	v_pk_fma_f32 v[162:163], v[110:111], v[144:145], v[150:151] op_sel_hi:[1,0,1]
	ds_read_b128 v[148:151], v142 offset:16400
	v_pk_fma_f32 v[152:153], v[108:109], v[144:145], v[152:153] op_sel_hi:[1,0,1]
	v_readlane_b32 s46, v254, 11
	v_readlane_b32 s47, v254, 12
	v_readlane_b32 s48, v254, 13
	s_waitcnt lgkmcnt(0)
	v_pk_fma_f32 v[108:109], v[108:109], v[148:149], v[130:131] op_sel_hi:[1,0,1]
	v_pk_fma_f32 v[110:111], v[110:111], v[148:149], v[128:129] op_sel_hi:[1,0,1]
	v_pk_fma_f32 v[128:129], v[112:113], v[132:133], v[156:157] op_sel:[0,1,0]
	v_pk_fma_f32 v[130:131], v[114:115], v[136:137], v[158:159] op_sel:[0,1,0]
	v_pk_fma_f32 v[132:133], v[112:113], v[136:137], v[160:161] op_sel:[0,1,0]
	v_pk_fma_f32 v[136:137], v[114:115], v[144:145], v[162:163] op_sel:[0,1,0]
	v_pk_fma_f32 v[144:145], v[112:113], v[144:145], v[152:153] op_sel:[0,1,0]
	v_pk_fma_f32 v[108:109], v[112:113], v[148:149], v[108:109] op_sel:[0,1,0]
	v_pk_fma_f32 v[110:111], v[114:115], v[148:149], v[110:111] op_sel:[0,1,0]
	s_waitcnt vmcnt(25)
	v_pk_fma_f32 v[112:113], v[106:107], v[122:123], v[124:125] op_sel_hi:[1,0,1]
	v_pk_fma_f32 v[114:115], v[104:105], v[122:123], v[120:121] op_sel_hi:[1,0,1]
	v_pk_fma_f32 v[124:125], v[104:105], v[134:135], v[128:129] op_sel_hi:[1,0,1]
	v_pk_fma_f32 v[128:129], v[104:105], v[138:139], v[132:133] op_sel_hi:[1,0,1]
	v_pk_fma_f32 v[132:133], v[104:105], v[146:147], v[144:145] op_sel_hi:[1,0,1]
	v_pk_fma_f32 v[104:105], v[104:105], v[150:151], v[108:109] op_sel_hi:[1,0,1]
	v_mov_b32_e32 v108, v123
	v_pk_fma_f32 v[120:121], v[106:107], v[134:135], v[126:127] op_sel_hi:[1,0,1]
	v_pk_fma_f32 v[126:127], v[106:107], v[138:139], v[130:131] op_sel_hi:[1,0,1]
	v_pk_fma_f32 v[130:131], v[106:107], v[146:147], v[136:137] op_sel_hi:[1,0,1]
	v_pk_fma_f32 v[106:107], v[106:107], v[150:151], v[110:111] op_sel_hi:[1,0,1]
	s_waitcnt vmcnt(24)
	v_pk_fma_f32 v[110:111], v[102:103], v[108:109], v[112:113] op_sel_hi:[1,0,1]
	v_mov_b32_e32 v112, v135
	v_pk_fma_f32 v[108:109], v[100:101], v[108:109], v[114:115] op_sel_hi:[1,0,1]
	v_pk_fma_f32 v[114:115], v[102:103], v[112:113], v[120:121] op_sel_hi:[1,0,1]
	v_mov_b32_e32 v120, v139
	v_pk_fma_f32 v[112:113], v[100:101], v[112:113], v[124:125] op_sel_hi:[1,0,1]
	v_pk_fma_f32 v[122:123], v[102:103], v[120:121], v[126:127] op_sel_hi:[1,0,1]
	v_pk_fma_f32 v[120:121], v[100:101], v[120:121], v[128:129] op_sel_hi:[1,0,1]
	v_mov_b32_e32 v124, v147
	v_mov_b32_e32 v128, v151
	v_pk_fma_f32 v[126:127], v[102:103], v[124:125], v[130:131] op_sel_hi:[1,0,1]
	v_pk_fma_f32 v[124:125], v[100:101], v[124:125], v[132:133] op_sel_hi:[1,0,1]
	v_pk_fma_f32 v[130:131], v[102:103], v[128:129], v[106:107] op_sel_hi:[1,0,1]
	v_pk_fma_f32 v[128:129], v[100:101], v[128:129], v[104:105] op_sel_hi:[1,0,1]
	ds_read_b128 v[100:103], v142 offset:4128
	ds_read_b128 v[104:107], v142 offset:8224
	s_waitcnt vmcnt(23)
	v_pk_fma_f32 v[132:133], v[94:95], v[116:117], v[110:111] op_sel_hi:[1,0,1]
	v_pk_fma_f32 v[134:135], v[92:93], v[116:117], v[108:109] op_sel_hi:[1,0,1]
	ds_read_b128 v[108:111], v142 offset:12320
	s_waitcnt lgkmcnt(2)
	v_pk_fma_f32 v[136:137], v[94:95], v[100:101], v[114:115] op_sel_hi:[1,0,1]
	v_pk_fma_f32 v[138:139], v[92:93], v[100:101], v[112:113] op_sel_hi:[1,0,1]
	ds_read_b128 v[112:115], v142 offset:16416
	s_waitcnt lgkmcnt(2)
	v_pk_fma_f32 v[122:123], v[94:95], v[104:105], v[122:123] op_sel_hi:[1,0,1]
	v_pk_fma_f32 v[120:121], v[92:93], v[104:105], v[120:121] op_sel_hi:[1,0,1]
	s_waitcnt lgkmcnt(1)
	v_pk_fma_f32 v[126:127], v[94:95], v[108:109], v[126:127] op_sel_hi:[1,0,1]
	v_pk_fma_f32 v[124:125], v[92:93], v[108:109], v[124:125] op_sel_hi:[1,0,1]
	s_waitcnt lgkmcnt(0)
	v_pk_fma_f32 v[92:93], v[92:93], v[112:113], v[128:129] op_sel_hi:[1,0,1]
	v_pk_fma_f32 v[94:95], v[94:95], v[112:113], v[130:131] op_sel_hi:[1,0,1]
	s_waitcnt vmcnt(22)
	v_pk_fma_f32 v[128:129], v[98:99], v[116:117], v[132:133] op_sel:[0,1,0]
	v_pk_fma_f32 v[116:117], v[96:97], v[116:117], v[134:135] op_sel:[0,1,0]
	v_pk_fma_f32 v[130:131], v[98:99], v[100:101], v[136:137] op_sel:[0,1,0]
	v_pk_fma_f32 v[100:101], v[96:97], v[100:101], v[138:139] op_sel:[0,1,0]
	v_pk_fma_f32 v[122:123], v[98:99], v[104:105], v[122:123] op_sel:[0,1,0]
	v_pk_fma_f32 v[104:105], v[96:97], v[104:105], v[120:121] op_sel:[0,1,0]
	v_pk_fma_f32 v[120:121], v[98:99], v[108:109], v[126:127] op_sel:[0,1,0]
	v_pk_fma_f32 v[108:109], v[96:97], v[108:109], v[124:125] op_sel:[0,1,0]
	v_pk_fma_f32 v[92:93], v[96:97], v[112:113], v[92:93] op_sel:[0,1,0]
	v_pk_fma_f32 v[94:95], v[98:99], v[112:113], v[94:95] op_sel:[0,1,0]
	s_waitcnt vmcnt(21)
	v_pk_fma_f32 v[96:97], v[90:91], v[118:119], v[128:129] op_sel_hi:[1,0,1]
	v_pk_fma_f32 v[98:99], v[88:89], v[118:119], v[116:117] op_sel_hi:[1,0,1]
	v_pk_fma_f32 v[100:101], v[88:89], v[102:103], v[100:101] op_sel_hi:[1,0,1]
	v_pk_fma_f32 v[104:105], v[88:89], v[106:107], v[104:105] op_sel_hi:[1,0,1]
	v_pk_fma_f32 v[108:109], v[88:89], v[110:111], v[108:109] op_sel_hi:[1,0,1]
	v_pk_fma_f32 v[92:93], v[88:89], v[114:115], v[92:93] op_sel_hi:[1,0,1]
	v_mov_b32_e32 v88, v119
	v_pk_fma_f32 v[112:113], v[90:91], v[102:103], v[130:131] op_sel_hi:[1,0,1]
	v_pk_fma_f32 v[116:117], v[90:91], v[106:107], v[122:123] op_sel_hi:[1,0,1]
	v_pk_fma_f32 v[120:121], v[90:91], v[110:111], v[120:121] op_sel_hi:[1,0,1]
	v_pk_fma_f32 v[90:91], v[90:91], v[114:115], v[94:95] op_sel_hi:[1,0,1]
	s_waitcnt vmcnt(20)
	v_pk_fma_f32 v[94:95], v[86:87], v[88:89], v[96:97] op_sel_hi:[1,0,1]
	v_pk_fma_f32 v[96:97], v[84:85], v[88:89], v[98:99] op_sel_hi:[1,0,1]
	v_mov_b32_e32 v88, v103
	v_pk_fma_f32 v[98:99], v[86:87], v[88:89], v[112:113] op_sel_hi:[1,0,1]
	v_pk_fma_f32 v[100:101], v[84:85], v[88:89], v[100:101] op_sel_hi:[1,0,1]
	v_mov_b32_e32 v88, v107
	v_pk_fma_f32 v[102:103], v[86:87], v[88:89], v[116:117] op_sel_hi:[1,0,1]
	v_pk_fma_f32 v[104:105], v[84:85], v[88:89], v[104:105] op_sel_hi:[1,0,1]
	v_mov_b32_e32 v88, v111
	v_mov_b32_e32 v110, v115
	v_pk_fma_f32 v[106:107], v[86:87], v[88:89], v[120:121] op_sel_hi:[1,0,1]
	v_pk_fma_f32 v[108:109], v[84:85], v[88:89], v[108:109] op_sel_hi:[1,0,1]
	v_pk_fma_f32 v[88:89], v[86:87], v[110:111], v[90:91] op_sel_hi:[1,0,1]
	v_pk_fma_f32 v[90:91], v[84:85], v[110:111], v[92:93] op_sel_hi:[1,0,1]
	s_waitcnt vmcnt(19)
	v_pk_fma_f32 v[84:85], v[74:75], v[80:81], v[94:95] op_sel_hi:[1,0,1]
	ds_read_b128 v[92:95], v142 offset:4144
	v_pk_fma_f32 v[86:87], v[72:73], v[80:81], v[96:97] op_sel_hi:[1,0,1]
	s_waitcnt vmcnt(18)
	v_pk_fma_f32 v[84:85], v[78:79], v[80:81], v[84:85] op_sel:[0,1,0]
	v_pk_fma_f32 v[80:81], v[76:77], v[80:81], v[86:87] op_sel:[0,1,0]
	v_readlane_b32 s49, v254, 14
	s_waitcnt lgkmcnt(0)
	v_pk_fma_f32 v[110:111], v[74:75], v[92:93], v[98:99] op_sel_hi:[1,0,1]
	ds_read_b128 v[96:99], v142 offset:8240
	v_pk_fma_f32 v[112:113], v[72:73], v[92:93], v[100:101] op_sel_hi:[1,0,1]
	v_pk_fma_f32 v[86:87], v[78:79], v[92:93], v[110:111] op_sel:[0,1,0]
	v_readlane_b32 s52, v254, 17
	v_readlane_b32 s53, v254, 18
	s_waitcnt lgkmcnt(0)
	v_pk_fma_f32 v[114:115], v[74:75], v[96:97], v[102:103] op_sel_hi:[1,0,1]
	ds_read_b128 v[100:103], v142 offset:12336
	v_pk_fma_f32 v[116:117], v[72:73], v[96:97], v[104:105] op_sel_hi:[1,0,1]
	v_readlane_b32 s54, v254, 19
	v_readlane_b32 s55, v254, 20
	s_waitcnt lgkmcnt(0)
	v_pk_fma_f32 v[118:119], v[74:75], v[100:101], v[106:107] op_sel_hi:[1,0,1]
	ds_read_b128 v[104:107], v142 offset:16432
	v_pk_fma_f32 v[108:109], v[72:73], v[100:101], v[108:109] op_sel_hi:[1,0,1]
	s_waitcnt lgkmcnt(0)
	v_pk_fma_f32 v[72:73], v[72:73], v[104:105], v[90:91] op_sel_hi:[1,0,1]
	v_pk_fma_f32 v[74:75], v[74:75], v[104:105], v[88:89] op_sel_hi:[1,0,1]
	v_pk_fma_f32 v[88:89], v[76:77], v[92:93], v[112:113] op_sel:[0,1,0]
	v_pk_fma_f32 v[90:91], v[78:79], v[96:97], v[114:115] op_sel:[0,1,0]
	v_pk_fma_f32 v[92:93], v[76:77], v[96:97], v[116:117] op_sel:[0,1,0]
	v_pk_fma_f32 v[96:97], v[78:79], v[100:101], v[118:119] op_sel:[0,1,0]
	v_pk_fma_f32 v[100:101], v[76:77], v[100:101], v[108:109] op_sel:[0,1,0]
	v_pk_fma_f32 v[72:73], v[76:77], v[104:105], v[72:73] op_sel:[0,1,0]
	v_pk_fma_f32 v[74:75], v[78:79], v[104:105], v[74:75] op_sel:[0,1,0]
	s_waitcnt vmcnt(17)
	v_pk_fma_f32 v[76:77], v[70:71], v[82:83], v[84:85] op_sel_hi:[1,0,1]
	v_pk_fma_f32 v[78:79], v[68:69], v[82:83], v[80:81] op_sel_hi:[1,0,1]
	v_pk_fma_f32 v[84:85], v[68:69], v[94:95], v[88:89] op_sel_hi:[1,0,1]
	v_pk_fma_f32 v[88:89], v[68:69], v[98:99], v[92:93] op_sel_hi:[1,0,1]
	v_pk_fma_f32 v[92:93], v[68:69], v[102:103], v[100:101] op_sel_hi:[1,0,1]
	v_pk_fma_f32 v[68:69], v[68:69], v[106:107], v[72:73] op_sel_hi:[1,0,1]
	v_mov_b32_e32 v72, v83
	v_pk_fma_f32 v[80:81], v[70:71], v[94:95], v[86:87] op_sel_hi:[1,0,1]
	v_pk_fma_f32 v[86:87], v[70:71], v[98:99], v[90:91] op_sel_hi:[1,0,1]
	v_pk_fma_f32 v[90:91], v[70:71], v[102:103], v[96:97] op_sel_hi:[1,0,1]
	v_pk_fma_f32 v[70:71], v[70:71], v[106:107], v[74:75] op_sel_hi:[1,0,1]
	s_waitcnt vmcnt(16)
	v_pk_fma_f32 v[74:75], v[66:67], v[72:73], v[76:77] op_sel_hi:[1,0,1]
	v_mov_b32_e32 v76, v95
	v_pk_fma_f32 v[72:73], v[64:65], v[72:73], v[78:79] op_sel_hi:[1,0,1]
	v_pk_fma_f32 v[78:79], v[66:67], v[76:77], v[80:81] op_sel_hi:[1,0,1]
	v_mov_b32_e32 v80, v99
	v_pk_fma_f32 v[76:77], v[64:65], v[76:77], v[84:85] op_sel_hi:[1,0,1]
	v_pk_fma_f32 v[82:83], v[66:67], v[80:81], v[86:87] op_sel_hi:[1,0,1]
	v_pk_fma_f32 v[80:81], v[64:65], v[80:81], v[88:89] op_sel_hi:[1,0,1]
	v_mov_b32_e32 v84, v103
	v_mov_b32_e32 v88, v107
	v_pk_fma_f32 v[86:87], v[66:67], v[84:85], v[90:91] op_sel_hi:[1,0,1]
	v_pk_fma_f32 v[84:85], v[64:65], v[84:85], v[92:93] op_sel_hi:[1,0,1]
	v_pk_fma_f32 v[90:91], v[66:67], v[88:89], v[70:71] op_sel_hi:[1,0,1]
	v_pk_fma_f32 v[88:89], v[64:65], v[88:89], v[68:69] op_sel_hi:[1,0,1]
	ds_read_b128 v[64:67], v142 offset:64
	ds_read_b128 v[68:71], v142 offset:4160
	s_waitcnt vmcnt(15) lgkmcnt(1)
	v_pk_fma_f32 v[92:93], v[58:59], v[64:65], v[74:75] op_sel_hi:[1,0,1]
	v_pk_fma_f32 v[94:95], v[56:57], v[64:65], v[72:73] op_sel_hi:[1,0,1]
	ds_read_b128 v[72:75], v142 offset:8256
	s_waitcnt lgkmcnt(1)
	v_pk_fma_f32 v[96:97], v[58:59], v[68:69], v[78:79] op_sel_hi:[1,0,1]
	v_pk_fma_f32 v[98:99], v[56:57], v[68:69], v[76:77] op_sel_hi:[1,0,1]
	ds_read_b128 v[76:79], v142 offset:12352
	s_waitcnt lgkmcnt(1)
	v_pk_fma_f32 v[100:101], v[58:59], v[72:73], v[82:83] op_sel_hi:[1,0,1]
	v_pk_fma_f32 v[102:103], v[56:57], v[72:73], v[80:81] op_sel_hi:[1,0,1]
	ds_read_b128 v[80:83], v142 offset:16448
	s_waitcnt lgkmcnt(1)
	v_pk_fma_f32 v[86:87], v[58:59], v[76:77], v[86:87] op_sel_hi:[1,0,1]
	v_pk_fma_f32 v[84:85], v[56:57], v[76:77], v[84:85] op_sel_hi:[1,0,1]
	s_waitcnt vmcnt(14)
	v_pk_fma_f32 v[86:87], v[62:63], v[76:77], v[86:87] op_sel:[0,1,0]
	v_pk_fma_f32 v[76:77], v[60:61], v[76:77], v[84:85] op_sel:[0,1,0]
	s_waitcnt lgkmcnt(0)
	v_pk_fma_f32 v[56:57], v[56:57], v[80:81], v[88:89] op_sel_hi:[1,0,1]
	v_pk_fma_f32 v[58:59], v[58:59], v[80:81], v[90:91] op_sel_hi:[1,0,1]
	v_pk_fma_f32 v[88:89], v[62:63], v[64:65], v[92:93] op_sel:[0,1,0]
	v_pk_fma_f32 v[64:65], v[60:61], v[64:65], v[94:95] op_sel:[0,1,0]
	v_pk_fma_f32 v[90:91], v[62:63], v[68:69], v[96:97] op_sel:[0,1,0]
	v_pk_fma_f32 v[68:69], v[60:61], v[68:69], v[98:99] op_sel:[0,1,0]
	v_pk_fma_f32 v[92:93], v[62:63], v[72:73], v[100:101] op_sel:[0,1,0]
	v_pk_fma_f32 v[72:73], v[60:61], v[72:73], v[102:103] op_sel:[0,1,0]
	v_pk_fma_f32 v[56:57], v[60:61], v[80:81], v[56:57] op_sel:[0,1,0]
	v_pk_fma_f32 v[58:59], v[62:63], v[80:81], v[58:59] op_sel:[0,1,0]
	s_waitcnt vmcnt(13)
	v_pk_fma_f32 v[60:61], v[54:55], v[66:67], v[88:89] op_sel_hi:[1,0,1]
	v_pk_fma_f32 v[62:63], v[52:53], v[66:67], v[64:65] op_sel_hi:[1,0,1]
	v_pk_fma_f32 v[68:69], v[52:53], v[70:71], v[68:69] op_sel_hi:[1,0,1]
	v_pk_fma_f32 v[72:73], v[52:53], v[74:75], v[72:73] op_sel_hi:[1,0,1]
	v_pk_fma_f32 v[76:77], v[52:53], v[78:79], v[76:77] op_sel_hi:[1,0,1]
	v_pk_fma_f32 v[56:57], v[52:53], v[82:83], v[56:57] op_sel_hi:[1,0,1]
	v_mov_b32_e32 v52, v67
	v_pk_fma_f32 v[64:65], v[54:55], v[70:71], v[90:91] op_sel_hi:[1,0,1]
	v_pk_fma_f32 v[80:81], v[54:55], v[74:75], v[92:93] op_sel_hi:[1,0,1]
	v_pk_fma_f32 v[84:85], v[54:55], v[78:79], v[86:87] op_sel_hi:[1,0,1]
	v_pk_fma_f32 v[54:55], v[54:55], v[82:83], v[58:59] op_sel_hi:[1,0,1]
	s_waitcnt vmcnt(12)
	v_pk_fma_f32 v[58:59], v[50:51], v[52:53], v[60:61] op_sel_hi:[1,0,1]
	v_pk_fma_f32 v[60:61], v[48:49], v[52:53], v[62:63] op_sel_hi:[1,0,1]
	v_mov_b32_e32 v52, v71
	v_pk_fma_f32 v[62:63], v[50:51], v[52:53], v[64:65] op_sel_hi:[1,0,1]
	v_pk_fma_f32 v[64:65], v[48:49], v[52:53], v[68:69] op_sel_hi:[1,0,1]
	v_mov_b32_e32 v52, v75
	v_pk_fma_f32 v[66:67], v[50:51], v[52:53], v[80:81] op_sel_hi:[1,0,1]
	v_pk_fma_f32 v[68:69], v[48:49], v[52:53], v[72:73] op_sel_hi:[1,0,1]
	v_mov_b32_e32 v52, v79
	v_mov_b32_e32 v74, v83
	v_pk_fma_f32 v[70:71], v[50:51], v[52:53], v[84:85] op_sel_hi:[1,0,1]
	v_pk_fma_f32 v[72:73], v[48:49], v[52:53], v[76:77] op_sel_hi:[1,0,1]
	v_pk_fma_f32 v[52:53], v[50:51], v[74:75], v[54:55] op_sel_hi:[1,0,1]
	v_pk_fma_f32 v[54:55], v[48:49], v[74:75], v[56:57] op_sel_hi:[1,0,1]
	ds_read_b128 v[48:51], v142 offset:80
	s_waitcnt vmcnt(11) lgkmcnt(0)
	v_pk_fma_f32 v[74:75], v[42:43], v[48:49], v[58:59] op_sel_hi:[1,0,1]
	ds_read_b128 v[56:59], v142 offset:4176
	v_pk_fma_f32 v[76:77], v[40:41], v[48:49], v[60:61] op_sel_hi:[1,0,1]
	s_waitcnt lgkmcnt(0)
	v_pk_fma_f32 v[78:79], v[42:43], v[56:57], v[62:63] op_sel_hi:[1,0,1]
	ds_read_b128 v[60:63], v142 offset:8272
	v_pk_fma_f32 v[80:81], v[40:41], v[56:57], v[64:65] op_sel_hi:[1,0,1]
	s_waitcnt lgkmcnt(0)
	v_pk_fma_f32 v[82:83], v[42:43], v[60:61], v[66:67] op_sel_hi:[1,0,1]
	ds_read_b128 v[64:67], v142 offset:12368
	v_pk_fma_f32 v[84:85], v[40:41], v[60:61], v[68:69] op_sel_hi:[1,0,1]
	s_waitcnt lgkmcnt(0)
	v_pk_fma_f32 v[86:87], v[42:43], v[64:65], v[70:71] op_sel_hi:[1,0,1]
	ds_read_b128 v[68:71], v142 offset:16464
	v_pk_fma_f32 v[72:73], v[40:41], v[64:65], v[72:73] op_sel_hi:[1,0,1]
	s_waitcnt lgkmcnt(0)
	v_pk_fma_f32 v[40:41], v[40:41], v[68:69], v[54:55] op_sel_hi:[1,0,1]
	v_pk_fma_f32 v[42:43], v[42:43], v[68:69], v[52:53] op_sel_hi:[1,0,1]
	s_waitcnt vmcnt(10)
	v_pk_fma_f32 v[52:53], v[46:47], v[48:49], v[74:75] op_sel:[0,1,0]
	v_pk_fma_f32 v[48:49], v[44:45], v[48:49], v[76:77] op_sel:[0,1,0]
	v_pk_fma_f32 v[54:55], v[46:47], v[56:57], v[78:79] op_sel:[0,1,0]
	v_pk_fma_f32 v[56:57], v[44:45], v[56:57], v[80:81] op_sel:[0,1,0]
	v_pk_fma_f32 v[74:75], v[46:47], v[60:61], v[82:83] op_sel:[0,1,0]
	v_pk_fma_f32 v[60:61], v[44:45], v[60:61], v[84:85] op_sel:[0,1,0]
	v_pk_fma_f32 v[76:77], v[46:47], v[64:65], v[86:87] op_sel:[0,1,0]
	v_pk_fma_f32 v[64:65], v[44:45], v[64:65], v[72:73] op_sel:[0,1,0]
	v_pk_fma_f32 v[40:41], v[44:45], v[68:69], v[40:41] op_sel:[0,1,0]
	v_pk_fma_f32 v[42:43], v[46:47], v[68:69], v[42:43] op_sel:[0,1,0]
	s_waitcnt vmcnt(9)
	v_pk_fma_f32 v[44:45], v[38:39], v[50:51], v[52:53] op_sel_hi:[1,0,1]
	v_pk_fma_f32 v[46:47], v[36:37], v[50:51], v[48:49] op_sel_hi:[1,0,1]
	v_pk_fma_f32 v[52:53], v[36:37], v[58:59], v[56:57] op_sel_hi:[1,0,1]
	v_pk_fma_f32 v[56:57], v[36:37], v[62:63], v[60:61] op_sel_hi:[1,0,1]
	v_pk_fma_f32 v[64:65], v[36:37], v[66:67], v[64:65] op_sel_hi:[1,0,1]
	v_pk_fma_f32 v[36:37], v[36:37], v[70:71], v[40:41] op_sel_hi:[1,0,1]
	v_mov_b32_e32 v40, v51
	v_pk_fma_f32 v[48:49], v[38:39], v[58:59], v[54:55] op_sel_hi:[1,0,1]
	v_pk_fma_f32 v[54:55], v[38:39], v[62:63], v[74:75] op_sel_hi:[1,0,1]
	v_pk_fma_f32 v[60:61], v[38:39], v[66:67], v[76:77] op_sel_hi:[1,0,1]
	v_pk_fma_f32 v[38:39], v[38:39], v[70:71], v[42:43] op_sel_hi:[1,0,1]
	s_waitcnt vmcnt(8)
	v_pk_fma_f32 v[42:43], v[34:35], v[40:41], v[44:45] op_sel_hi:[1,0,1]
	v_mov_b32_e32 v44, v59
	v_pk_fma_f32 v[40:41], v[32:33], v[40:41], v[46:47] op_sel_hi:[1,0,1]
	v_pk_fma_f32 v[46:47], v[34:35], v[44:45], v[48:49] op_sel_hi:[1,0,1]
	v_mov_b32_e32 v48, v63
	v_pk_fma_f32 v[44:45], v[32:33], v[44:45], v[52:53] op_sel_hi:[1,0,1]
	v_pk_fma_f32 v[50:51], v[34:35], v[48:49], v[54:55] op_sel_hi:[1,0,1]
	v_pk_fma_f32 v[48:49], v[32:33], v[48:49], v[56:57] op_sel_hi:[1,0,1]
	v_mov_b32_e32 v52, v67
	v_mov_b32_e32 v56, v71
	v_pk_fma_f32 v[54:55], v[34:35], v[52:53], v[60:61] op_sel_hi:[1,0,1]
	v_pk_fma_f32 v[52:53], v[32:33], v[52:53], v[64:65] op_sel_hi:[1,0,1]
	v_pk_fma_f32 v[58:59], v[34:35], v[56:57], v[38:39] op_sel_hi:[1,0,1]
	v_pk_fma_f32 v[56:57], v[32:33], v[56:57], v[36:37] op_sel_hi:[1,0,1]
	ds_read_b128 v[32:35], v142 offset:96
	ds_read_b128 v[36:39], v142 offset:4192
	s_waitcnt vmcnt(7) lgkmcnt(1)
	v_pk_fma_f32 v[60:61], v[26:27], v[32:33], v[42:43] op_sel_hi:[1,0,1]
	v_pk_fma_f32 v[62:63], v[24:25], v[32:33], v[40:41] op_sel_hi:[1,0,1]
	ds_read_b128 v[40:43], v142 offset:8288
	s_waitcnt lgkmcnt(1)
	v_pk_fma_f32 v[64:65], v[26:27], v[36:37], v[46:47] op_sel_hi:[1,0,1]
	v_pk_fma_f32 v[66:67], v[24:25], v[36:37], v[44:45] op_sel_hi:[1,0,1]
	ds_read_b128 v[44:47], v142 offset:12384
	s_waitcnt lgkmcnt(1)
	v_pk_fma_f32 v[68:69], v[26:27], v[40:41], v[50:51] op_sel_hi:[1,0,1]
	v_pk_fma_f32 v[70:71], v[24:25], v[40:41], v[48:49] op_sel_hi:[1,0,1]
	ds_read_b128 v[48:51], v142 offset:16480
	s_waitcnt lgkmcnt(1)
	v_pk_fma_f32 v[54:55], v[26:27], v[44:45], v[54:55] op_sel_hi:[1,0,1]
	v_pk_fma_f32 v[52:53], v[24:25], v[44:45], v[52:53] op_sel_hi:[1,0,1]
	s_waitcnt vmcnt(6)
	v_pk_fma_f32 v[54:55], v[30:31], v[44:45], v[54:55] op_sel:[0,1,0]
	v_pk_fma_f32 v[44:45], v[28:29], v[44:45], v[52:53] op_sel:[0,1,0]
	s_waitcnt lgkmcnt(0)
	v_pk_fma_f32 v[24:25], v[24:25], v[48:49], v[56:57] op_sel_hi:[1,0,1]
	v_pk_fma_f32 v[26:27], v[26:27], v[48:49], v[58:59] op_sel_hi:[1,0,1]
	v_pk_fma_f32 v[56:57], v[30:31], v[32:33], v[60:61] op_sel:[0,1,0]
	v_pk_fma_f32 v[32:33], v[28:29], v[32:33], v[62:63] op_sel:[0,1,0]
	v_pk_fma_f32 v[58:59], v[30:31], v[36:37], v[64:65] op_sel:[0,1,0]
	v_pk_fma_f32 v[36:37], v[28:29], v[36:37], v[66:67] op_sel:[0,1,0]
	v_pk_fma_f32 v[60:61], v[30:31], v[40:41], v[68:69] op_sel:[0,1,0]
	v_pk_fma_f32 v[40:41], v[28:29], v[40:41], v[70:71] op_sel:[0,1,0]
	v_pk_fma_f32 v[24:25], v[28:29], v[48:49], v[24:25] op_sel:[0,1,0]
	v_pk_fma_f32 v[26:27], v[30:31], v[48:49], v[26:27] op_sel:[0,1,0]
	s_waitcnt vmcnt(5)
	v_pk_fma_f32 v[28:29], v[22:23], v[34:35], v[56:57] op_sel_hi:[1,0,1]
	v_pk_fma_f32 v[30:31], v[20:21], v[34:35], v[32:33] op_sel_hi:[1,0,1]
	v_pk_fma_f32 v[36:37], v[20:21], v[38:39], v[36:37] op_sel_hi:[1,0,1]
	v_pk_fma_f32 v[40:41], v[20:21], v[42:43], v[40:41] op_sel_hi:[1,0,1]
	v_pk_fma_f32 v[44:45], v[20:21], v[46:47], v[44:45] op_sel_hi:[1,0,1]
	v_pk_fma_f32 v[24:25], v[20:21], v[50:51], v[24:25] op_sel_hi:[1,0,1]
	v_mov_b32_e32 v20, v35
	v_pk_fma_f32 v[32:33], v[22:23], v[38:39], v[58:59] op_sel_hi:[1,0,1]
	v_pk_fma_f32 v[48:49], v[22:23], v[42:43], v[60:61] op_sel_hi:[1,0,1]
	v_pk_fma_f32 v[52:53], v[22:23], v[46:47], v[54:55] op_sel_hi:[1,0,1]
	v_pk_fma_f32 v[22:23], v[22:23], v[50:51], v[26:27] op_sel_hi:[1,0,1]
	s_waitcnt vmcnt(4)
	v_pk_fma_f32 v[26:27], v[18:19], v[20:21], v[28:29] op_sel_hi:[1,0,1]
	v_pk_fma_f32 v[28:29], v[16:17], v[20:21], v[30:31] op_sel_hi:[1,0,1]
	v_mov_b32_e32 v20, v39
	v_pk_fma_f32 v[30:31], v[18:19], v[20:21], v[32:33] op_sel_hi:[1,0,1]
	v_pk_fma_f32 v[32:33], v[16:17], v[20:21], v[36:37] op_sel_hi:[1,0,1]
	v_mov_b32_e32 v20, v43
	v_pk_fma_f32 v[34:35], v[18:19], v[20:21], v[48:49] op_sel_hi:[1,0,1]
	v_pk_fma_f32 v[36:37], v[16:17], v[20:21], v[40:41] op_sel_hi:[1,0,1]
	v_mov_b32_e32 v20, v47
	v_mov_b32_e32 v42, v51
	v_pk_fma_f32 v[38:39], v[18:19], v[20:21], v[52:53] op_sel_hi:[1,0,1]
	v_pk_fma_f32 v[40:41], v[16:17], v[20:21], v[44:45] op_sel_hi:[1,0,1]
	v_pk_fma_f32 v[20:21], v[18:19], v[42:43], v[22:23] op_sel_hi:[1,0,1]
	v_pk_fma_f32 v[22:23], v[16:17], v[42:43], v[24:25] op_sel_hi:[1,0,1]
	ds_read_b128 v[16:19], v142 offset:112
	s_waitcnt vmcnt(3) lgkmcnt(0)
	v_pk_fma_f32 v[42:43], v[10:11], v[16:17], v[26:27] op_sel_hi:[1,0,1]
	ds_read_b128 v[24:27], v142 offset:4208
	v_pk_fma_f32 v[44:45], v[8:9], v[16:17], v[28:29] op_sel_hi:[1,0,1]
	s_waitcnt lgkmcnt(0)
	v_pk_fma_f32 v[46:47], v[10:11], v[24:25], v[30:31] op_sel_hi:[1,0,1]
	ds_read_b128 v[28:31], v142 offset:8304
	v_pk_fma_f32 v[48:49], v[8:9], v[24:25], v[32:33] op_sel_hi:[1,0,1]
	s_waitcnt lgkmcnt(0)
	v_pk_fma_f32 v[50:51], v[10:11], v[28:29], v[34:35] op_sel_hi:[1,0,1]
	ds_read_b128 v[32:35], v142 offset:12400
	v_pk_fma_f32 v[52:53], v[8:9], v[28:29], v[36:37] op_sel_hi:[1,0,1]
	s_waitcnt lgkmcnt(0)
	v_pk_fma_f32 v[54:55], v[10:11], v[32:33], v[38:39] op_sel_hi:[1,0,1]
	ds_read_b128 v[36:39], v142 offset:16496
	v_pk_fma_f32 v[40:41], v[8:9], v[32:33], v[40:41] op_sel_hi:[1,0,1]
	s_waitcnt lgkmcnt(0)
	v_pk_fma_f32 v[8:9], v[8:9], v[36:37], v[22:23] op_sel_hi:[1,0,1]
	v_pk_fma_f32 v[10:11], v[10:11], v[36:37], v[20:21] op_sel_hi:[1,0,1]
	s_waitcnt vmcnt(2)
	v_pk_fma_f32 v[20:21], v[14:15], v[16:17], v[42:43] op_sel:[0,1,0]
	v_pk_fma_f32 v[16:17], v[12:13], v[16:17], v[44:45] op_sel:[0,1,0]
	v_pk_fma_f32 v[22:23], v[14:15], v[24:25], v[46:47] op_sel:[0,1,0]
	v_pk_fma_f32 v[24:25], v[12:13], v[24:25], v[48:49] op_sel:[0,1,0]
	v_pk_fma_f32 v[42:43], v[14:15], v[28:29], v[50:51] op_sel:[0,1,0]
	v_pk_fma_f32 v[28:29], v[12:13], v[28:29], v[52:53] op_sel:[0,1,0]
	v_pk_fma_f32 v[44:45], v[14:15], v[32:33], v[54:55] op_sel:[0,1,0]
	v_pk_fma_f32 v[32:33], v[12:13], v[32:33], v[40:41] op_sel:[0,1,0]
	v_pk_fma_f32 v[8:9], v[12:13], v[36:37], v[8:9] op_sel:[0,1,0]
	v_pk_fma_f32 v[10:11], v[14:15], v[36:37], v[10:11] op_sel:[0,1,0]
	s_waitcnt vmcnt(1)
	v_pk_fma_f32 v[12:13], v[6:7], v[18:19], v[20:21] op_sel_hi:[1,0,1]
	v_pk_fma_f32 v[14:15], v[4:5], v[18:19], v[16:17] op_sel_hi:[1,0,1]
	v_pk_fma_f32 v[16:17], v[6:7], v[26:27], v[22:23] op_sel_hi:[1,0,1]
	v_pk_fma_f32 v[20:21], v[4:5], v[26:27], v[24:25] op_sel_hi:[1,0,1]
	v_pk_fma_f32 v[24:25], v[4:5], v[30:31], v[28:29] op_sel_hi:[1,0,1]
	v_pk_fma_f32 v[32:33], v[4:5], v[34:35], v[32:33] op_sel_hi:[1,0,1]
	v_pk_fma_f32 v[40:41], v[4:5], v[38:39], v[8:9] op_sel_hi:[1,0,1]
	v_mov_b32_e32 v4, v19
	v_mov_b32_e32 v8, v27
	v_pk_fma_f32 v[22:23], v[6:7], v[30:31], v[42:43] op_sel_hi:[1,0,1]
	v_pk_fma_f32 v[28:29], v[6:7], v[34:35], v[44:45] op_sel_hi:[1,0,1]
	v_pk_fma_f32 v[36:37], v[6:7], v[38:39], v[10:11] op_sel_hi:[1,0,1]
	s_waitcnt vmcnt(0)
	v_pk_fma_f32 v[6:7], v[2:3], v[4:5], v[12:13] op_sel_hi:[1,0,1]
	v_pk_fma_f32 v[10:11], v[2:3], v[8:9], v[16:17] op_sel_hi:[1,0,1]
	v_pk_fma_f32 v[8:9], v[0:1], v[8:9], v[20:21] op_sel_hi:[1,0,1]
	v_mov_b32_e32 v12, v31
	v_mov_b32_e32 v16, v35
	v_mov_b32_e32 v20, v39
	v_pk_fma_f32 v[4:5], v[0:1], v[4:5], v[14:15] op_sel_hi:[1,0,1]
	v_pk_fma_f32 v[14:15], v[2:3], v[12:13], v[22:23] op_sel_hi:[1,0,1]
	v_pk_fma_f32 v[12:13], v[0:1], v[12:13], v[24:25] op_sel_hi:[1,0,1]
	v_pk_fma_f32 v[18:19], v[2:3], v[16:17], v[28:29] op_sel_hi:[1,0,1]
	v_pk_fma_f32 v[16:17], v[0:1], v[16:17], v[32:33] op_sel_hi:[1,0,1]
	v_pk_fma_f32 v[2:3], v[2:3], v[20:21], v[36:37] op_sel_hi:[1,0,1]
	v_pk_fma_f32 v[0:1], v[0:1], v[20:21], v[40:41] op_sel_hi:[1,0,1]
	v_mul_lo_u32 v20, v141, s2
	v_add3_u32 v20, s69, v200, v20
	ds_write_b128 v20, v[4:7] offset:20480
	ds_write_b128 v20, v[8:11] offset:20608
	ds_write_b128 v20, v[12:15] offset:20736
	ds_write_b128 v20, v[16:19] offset:20864
	ds_write_b128 v20, v[0:3] offset:20992
	s_waitcnt lgkmcnt(0)
	s_barrier
	s_movk_i32 s2, 0xa0
	v_cmp_gt_i32_e32 vcc, s2, v140
	s_and_saveexec_b64 s[2:3], vcc
	s_cbranch_execz .LBB0_863
	v_readlane_b32 s28, v254, 21
	v_readlane_b32 s29, v254, 22
	v_and_b32_e32 v2, 31, v140
	s_andn2_b64 vcc, exec, s[28:29]
	s_cbranch_vccnz .LBB0_867
	s_mul_i32 s28, s36, 0x1800
	s_ashr_i32 s29, s28, 31
	v_readlane_b32 s40, v254, 5
	s_lshl_b64 s[28:29], s[28:29], 2
	v_readlane_b32 s52, v254, 17
	v_readlane_b32 s53, v254, 18
	s_add_u32 s28, s52, s28
	v_or_b32_e32 v0, s0, v2
	s_addc_u32 s29, s53, s29
	v_ashrrev_i32_e32 v1, 31, v0
	v_lshl_add_u64 v[0:1], v[0:1], 2, s[28:29]
	global_load_dword v1, v[0:1], off
	v_readlane_b32 s41, v254, 6
	v_readlane_b32 s42, v254, 7
	v_readlane_b32 s43, v254, 8
	v_readlane_b32 s44, v254, 9
	v_readlane_b32 s45, v254, 10
	v_readlane_b32 s46, v254, 11
	v_readlane_b32 s47, v254, 12
	v_readlane_b32 s48, v254, 13
	v_readlane_b32 s49, v254, 14
	v_readlane_b32 s50, v254, 15
	v_readlane_b32 s51, v254, 16
	v_readlane_b32 s54, v254, 19
	v_readlane_b32 s55, v254, 20
	s_branch .LBB0_868

.LBB0_884:
	v_ashrrev_i32_e32 v18, 4, v16
	v_add_u32_e32 v10, s36, v18
	v_ashrrev_i32_e32 v0, 31, v10
	v_mul_lo_u32 v2, s40, v0
	v_mul_lo_u32 v3, s41, v10
	s_waitcnt lgkmcnt(0)
	v_mad_u64_u32 v[0:1], s[42:43], s40, v10, 0
	v_add_u32_e32 v8, 32, v10
	v_add3_u32 v1, v1, v2, v3
	v_lshlrev_b32_e32 v2, 2, v16
	v_ashrrev_i32_e32 v9, 31, v8
	v_and_b32_e32 v24, 60, v2
	v_add_u32_e32 v2, 16, v10
	v_mul_lo_u32 v11, s40, v9
	v_mul_lo_u32 v12, s41, v8
	v_mad_u64_u32 v[8:9], s[44:45], s40, v8, 0
	v_add_u32_e32 v10, 48, v10
	v_ashrrev_i32_e32 v3, 31, v2
	v_add3_u32 v9, v9, v11, v12
	v_ashrrev_i32_e32 v11, 31, v10
	v_mul_lo_u32 v4, s40, v3
	v_mul_lo_u32 v5, s41, v2
	v_mad_u64_u32 v[2:3], s[44:45], s40, v2, 0
	v_mul_lo_u32 v12, s40, v11
	v_mul_lo_u32 v13, s41, v10
	v_mad_u64_u32 v[10:11], s[40:41], s40, v10, 0
	s_ashr_i32 s3, s2, 31
	v_add3_u32 v3, v3, v4, v5
	v_add3_u32 v11, v11, v12, v13
	v_lshl_add_u64 v[0:1], v[0:1], 2, s[38:39]
	s_lshl_b64 s[42:43], s[2:3], 2
	v_lshl_add_u64 v[2:3], v[2:3], 2, s[38:39]
	v_lshl_add_u64 v[8:9], v[8:9], 2, s[38:39]
	v_lshl_add_u64 v[10:11], v[10:11], 2, s[38:39]
	v_lshl_add_u64 v[0:1], v[0:1], 0, s[42:43]
	v_lshlrev_b32_e32 v200, 2, v24
	v_lshl_add_u64 v[2:3], v[2:3], 0, s[42:43]
	v_lshl_add_u64 v[8:9], v[8:9], 0, s[42:43]
	v_lshl_add_u64 v[10:11], v[10:11], 0, s[42:43]
	v_lshl_add_u64 v[0:1], v[0:1], 0, v[200:201]
	v_lshl_add_u64 v[2:3], v[2:3], 0, v[200:201]
	v_lshl_add_u64 v[8:9], v[8:9], 0, v[200:201]
	v_lshl_add_u64 v[10:11], v[10:11], 0, v[200:201]
	global_load_dwordx4 v[4:7], v[0:1], off nt
	s_nop 0
	global_load_dwordx4 v[0:3], v[2:3], off nt
	s_nop 0
	global_load_dwordx4 v[12:15], v[8:9], off nt
	s_nop 0
	global_load_dwordx4 v[8:11], v[10:11], off nt
	s_movk_i32 s3, 0x104
	v_mul_lo_u32 v17, v18, s3
	v_add3_u32 v19, s69, v17, v200
	v_lshlrev_b32_e32 v17, 3, v16
	v_and_b32_e32 v26, 56, v17
	v_ashrrev_i32_e32 v20, 3, v16
	v_mul_u32_u24_e32 v17, 0x41, v26
	v_add_u32_e32 v16, 0x100, v16
	v_lshl_add_u32 v17, v17, 2, s69
	v_ashrrev_i32_e32 v22, 3, v16
	v_readlane_b32 s30, v255, 57
	s_nop 3
	s_lshl_b32 s33, s30, 4
	s_lshl_b32 s30, s30, 6
	s_lshl_b32 s37, s28, 4
	v_lshl_add_u32 v21, v20, 2, v17
	v_lshl_add_u32 v23, v22, 2, v17
	s_lshl_b32 s3, s28, 6
	s_add_i32 s50, s33, s37
	v_mov_b32_e32 v17, 0
	v_lshlrev_b32_e32 v200, 2, v24
	v_lshlrev_b32_e32 v16, 1, v26
	s_mov_b32 s51, s30
	v_mov_b32_e32 v24, 0
	v_mov_b32_e32 v25, 0
	v_mov_b32_e32 v26, 0
	v_mov_b32_e32 v27, 0
	v_mov_b32_e32 v28, 0
	v_mov_b32_e32 v29, 0
	v_mov_b32_e32 v30, 0
	v_mov_b32_e32 v31, 0
	v_mov_b32_e32 v32, 0
	v_mov_b32_e32 v33, 0
	v_mov_b32_e32 v34, 0
	v_mov_b32_e32 v35, 0
	v_mov_b32_e32 v36, 0
	v_mov_b32_e32 v37, 0
	v_mov_b32_e32 v38, 0
	s_mov_b64 s[38:39], s[0:1]
	s_mov_b32 s52, s29
	s_branch .LBB0_887
.LBB0_885:
	v_add_u32_e32 v10, s53, v18
	v_ashrrev_i32_e32 v0, 31, v10
	v_add_u32_e32 v8, 32, v10
	v_mul_lo_u32 v2, s46, v0
	v_mul_lo_u32 v3, s47, v10
	v_mad_u64_u32 v[0:1], s[48:49], s46, v10, 0
	v_ashrrev_i32_e32 v9, 31, v8
	v_add3_u32 v1, v1, v2, v3
	v_add_u32_e32 v2, 16, v10
	v_mul_lo_u32 v11, s46, v9
	v_mul_lo_u32 v12, s47, v8
	v_mad_u64_u32 v[8:9], s[54:55], s46, v8, 0
	v_add_u32_e32 v10, 48, v10
	v_ashrrev_i32_e32 v3, 31, v2
	v_add3_u32 v9, v9, v11, v12
	v_ashrrev_i32_e32 v11, 31, v10
	v_mul_lo_u32 v4, s46, v3
	v_mul_lo_u32 v5, s47, v2
	v_mad_u64_u32 v[2:3], s[54:55], s46, v2, 0
	v_mul_lo_u32 v12, s46, v11
	v_mul_lo_u32 v13, s47, v10
	v_mad_u64_u32 v[10:11], s[46:47], s46, v10, 0
	s_ashr_i32 s43, s42, 31
	v_add3_u32 v3, v3, v4, v5
	v_add3_u32 v11, v11, v12, v13
	v_lshl_add_u64 v[0:1], v[0:1], 2, s[44:45]
	s_lshl_b64 s[48:49], s[42:43], 2
	v_lshl_add_u64 v[2:3], v[2:3], 2, s[44:45]
	v_lshl_add_u64 v[8:9], v[8:9], 2, s[44:45]
	v_lshl_add_u64 v[10:11], v[10:11], 2, s[44:45]
	v_lshl_add_u64 v[0:1], v[0:1], 0, s[48:49]
	v_lshl_add_u64 v[2:3], v[2:3], 0, s[48:49]
	v_lshl_add_u64 v[8:9], v[8:9], 0, s[48:49]
	v_lshl_add_u64 v[10:11], v[10:11], 0, s[48:49]
	v_lshl_add_u64 v[0:1], v[0:1], 0, v[200:201]
	v_lshl_add_u64 v[2:3], v[2:3], 0, v[200:201]
	v_lshl_add_u64 v[8:9], v[8:9], 0, v[200:201]
	v_lshl_add_u64 v[10:11], v[10:11], 0, v[200:201]
	global_load_dwordx4 v[4:7], v[0:1], off nt
	s_nop 0
	global_load_dwordx4 v[0:3], v[2:3], off nt
	s_nop 0
	global_load_dwordx4 v[12:15], v[8:9], off nt
	s_nop 0
	global_load_dwordx4 v[8:11], v[10:11], off nt
